# FoX loop: per-tile row-max removed, lazy reference move decided after the tile from its row sum (threshold 2^24); sel staging addresses via scalar tile offset
# speedup vs baseline: 1.0055x; 1.0007x over previous
.LBB0_788:
	s_waitcnt lgkmcnt(0)
	s_barrier
	s_add_i32 s13, s13, 2
	s_add_i32 s19, s19, 8
	v_add_f32_e32 v0, v84, v85
	s_cmp_ge_i32 s21, s12
	v_add_f32_e32 v86, v176, v0
	s_mov_b64 s[8:9], 0
	s_cselect_b64 s[10:11], -1, 0
	v_cmp_lt_f32_e32 vcc, 0x4b800000, v0
	s_cbranch_vccz .Lfox_noresc2
	s_nop 13
	v_log_f32_e32 v2, v0
	s_nop 0
	v_max_f32_e32 v2, 0, v2
	v_exp_f32_e64 v84, -v2
	v_sub_f32_e32 v4, v4, v2
	v_sub_f32_e32 v5, v5, v2
	v_sub_f32_e32 v6, v6, v2
	v_sub_f32_e32 v7, v7, v2
	v_sub_f32_e32 v8, v8, v2
	v_sub_f32_e32 v9, v9, v2
	v_sub_f32_e32 v10, v10, v2
	v_sub_f32_e32 v11, v11, v2
	v_sub_f32_e32 v12, v12, v2
	v_sub_f32_e32 v13, v13, v2
	v_sub_f32_e32 v14, v14, v2
	v_sub_f32_e32 v15, v15, v2
	v_sub_f32_e32 v16, v16, v2
	v_sub_f32_e32 v17, v17, v2
	v_sub_f32_e32 v18, v18, v2
	v_sub_f32_e32 v19, v19, v2
	v_mul_f32_e32 v86, v86, v84
	v_pk_mul_f32 v[20:21], v[20:21], v[84:85] op_sel_hi:[1,0]
	v_pk_mul_f32 v[22:23], v[22:23], v[84:85] op_sel_hi:[1,0]
	v_pk_mul_f32 v[24:25], v[24:25], v[84:85] op_sel_hi:[1,0]
	v_pk_mul_f32 v[26:27], v[26:27], v[84:85] op_sel_hi:[1,0]
	v_pk_mul_f32 v[28:29], v[28:29], v[84:85] op_sel_hi:[1,0]
	v_pk_mul_f32 v[30:31], v[30:31], v[84:85] op_sel_hi:[1,0]
	v_pk_mul_f32 v[32:33], v[32:33], v[84:85] op_sel_hi:[1,0]
	v_pk_mul_f32 v[34:35], v[34:35], v[84:85] op_sel_hi:[1,0]
	v_pk_mul_f32 v[36:37], v[36:37], v[84:85] op_sel_hi:[1,0]
	v_pk_mul_f32 v[38:39], v[38:39], v[84:85] op_sel_hi:[1,0]
	v_pk_mul_f32 v[40:41], v[40:41], v[84:85] op_sel_hi:[1,0]
	v_pk_mul_f32 v[42:43], v[42:43], v[84:85] op_sel_hi:[1,0]
	v_pk_mul_f32 v[44:45], v[44:45], v[84:85] op_sel_hi:[1,0]
	v_pk_mul_f32 v[46:47], v[46:47], v[84:85] op_sel_hi:[1,0]
	v_pk_mul_f32 v[48:49], v[48:49], v[84:85] op_sel_hi:[1,0]
	v_pk_mul_f32 v[50:51], v[50:51], v[84:85] op_sel_hi:[1,0]
	s_nop 1
.Lfox_noresc2:
.LBB0_789:
	s_and_b64 vcc, exec, s[10:11]
	s_cbranch_vccnz .LBB0_815

.LBB0_794:
	s_mul_i32 s8, s17, 0x4900
	s_add_i32 s20, s33, s8
	v_add_u32_e32 v0, s20, v173
	v_add_u32_e32 v0, v0, v156
	ds_read_b128 v[52:55], v0
	ds_read_b128 v[88:91], v0 offset:32
	ds_read_b128 v[92:95], v0 offset:4608
	ds_read_b128 v[96:99], v0 offset:4640
	ds_read_b128 v[100:103], v0 offset:64
	ds_read_b128 v[104:107], v0 offset:96
	ds_read_b128 v[108:111], v0 offset:4672
	ds_read_b128 v[112:115], v0 offset:4704
	s_waitcnt lgkmcnt(7)
	v_mfma_f32_32x32x16_bf16 v[68:83], v[52:55], v[116:119], v[4:19]
	s_waitcnt lgkmcnt(5)
	v_mfma_f32_32x32x16_bf16 v[52:67], v[92:95], v[116:119], v[4:19]
	v_mfma_f32_32x32x16_bf16 v[68:83], v[88:91], v[120:123], v[68:83]
	ds_read_b128 v[88:91], v0 offset:128
	ds_read_b128 v[92:95], v0 offset:4736
	s_waitcnt lgkmcnt(6)
	v_mfma_f32_32x32x16_bf16 v[52:67], v[96:99], v[120:123], v[52:67]
	s_waitcnt lgkmcnt(5)
	v_mfma_f32_32x32x16_bf16 v[68:83], v[100:103], v[124:127], v[68:83]
	s_waitcnt lgkmcnt(3)
	v_mfma_f32_32x32x16_bf16 v[52:67], v[108:111], v[124:127], v[52:67]
	v_mfma_f32_32x32x16_bf16 v[68:83], v[104:107], v[128:131], v[68:83]
	s_waitcnt lgkmcnt(2)
	v_mfma_f32_32x32x16_bf16 v[52:67], v[112:115], v[128:131], v[52:67]
	s_waitcnt lgkmcnt(1)
	v_mfma_f32_32x32x16_bf16 v[68:83], v[88:91], v[148:151], v[68:83]
	s_waitcnt lgkmcnt(0)
	v_mfma_f32_32x32x16_bf16 v[52:67], v[92:95], v[148:151], v[52:67]
	v_mov_b32_e32 v2, s19
	ds_read_b32 v2, v2
	s_waitcnt lgkmcnt(0)
	v_cmp_gt_i32_e32 vcc, s18, v2
	s_cbranch_vccnz .LBB0_796
	v_lshl_or_b32 v2, v2, 6, v158
	v_or_b32_e32 v3, 32, v2
	v_cmp_le_i32_e32 vcc, v2, v154
	v_or_b32_e32 v84, 34, v2
	s_nop 0
	v_cndmask_b32_e32 v68, v185, v68, vcc
	v_cmp_le_i32_e32 vcc, v3, v154
	v_or_b32_e32 v3, 33, v2
	s_nop 0
	v_cndmask_b32_e32 v52, v185, v52, vcc
	v_cmp_lt_i32_e32 vcc, v2, v154
	s_nop 1
	v_cndmask_b32_e32 v69, v185, v69, vcc
	v_cmp_le_i32_e32 vcc, v3, v154
	v_or_b32_e32 v3, 2, v2
	s_nop 0
	v_cndmask_b32_e32 v53, v185, v53, vcc
	v_cmp_le_i32_e32 vcc, v3, v154
	v_or_b32_e32 v3, 3, v2
	s_nop 0
	v_cndmask_b32_e32 v70, v185, v70, vcc
	v_cmp_le_i32_e32 vcc, v84, v154
	v_or_b32_e32 v84, 35, v2
	s_nop 0
	v_cndmask_b32_e32 v54, v185, v54, vcc
	v_cmp_le_i32_e32 vcc, v3, v154
	v_or_b32_e32 v3, 8, v2
	s_nop 0
	v_cndmask_b32_e32 v71, v185, v71, vcc
	v_cmp_le_i32_e32 vcc, v84, v154
	v_or_b32_e32 v84, 40, v2
	s_nop 0
	v_cndmask_b32_e32 v55, v185, v55, vcc
	v_cmp_le_i32_e32 vcc, v3, v154
	v_or_b32_e32 v3, 9, v2
	s_nop 0
	v_cndmask_b32_e32 v72, v185, v72, vcc
	v_cmp_le_i32_e32 vcc, v84, v154
	v_or_b32_e32 v84, 41, v2
	s_nop 0
	v_cndmask_b32_e32 v56, v185, v56, vcc
	v_cmp_le_i32_e32 vcc, v3, v154
	v_or_b32_e32 v3, 10, v2
	s_nop 0
	v_cndmask_b32_e32 v73, v185, v73, vcc
	v_cmp_le_i32_e32 vcc, v84, v154
	v_or_b32_e32 v84, 42, v2
	s_nop 0
	v_cndmask_b32_e32 v57, v185, v57, vcc
	v_cmp_le_i32_e32 vcc, v3, v154
	v_or_b32_e32 v3, 11, v2
	s_nop 0
	v_cndmask_b32_e32 v74, v185, v74, vcc
	v_cmp_le_i32_e32 vcc, v84, v154
	v_or_b32_e32 v84, 43, v2
	s_nop 0
	v_cndmask_b32_e32 v58, v185, v58, vcc
	v_cmp_le_i32_e32 vcc, v3, v154
	v_or_b32_e32 v3, 16, v2
	s_nop 0
	v_cndmask_b32_e32 v75, v185, v75, vcc
	v_cmp_le_i32_e32 vcc, v84, v154
	v_or_b32_e32 v84, 48, v2
	s_nop 0
	v_cndmask_b32_e32 v59, v185, v59, vcc
	v_cmp_le_i32_e32 vcc, v3, v154
	v_or_b32_e32 v3, 17, v2
	s_nop 0
	v_cndmask_b32_e32 v76, v185, v76, vcc
	v_cmp_le_i32_e32 vcc, v84, v154
	v_or_b32_e32 v84, 49, v2
	s_nop 0
	v_cndmask_b32_e32 v60, v185, v60, vcc
	v_cmp_le_i32_e32 vcc, v3, v154
	v_or_b32_e32 v3, 18, v2
	s_nop 0
	v_cndmask_b32_e32 v77, v185, v77, vcc
	v_cmp_le_i32_e32 vcc, v84, v154
	v_or_b32_e32 v84, 50, v2
	s_nop 0
	v_cndmask_b32_e32 v61, v185, v61, vcc
	v_cmp_le_i32_e32 vcc, v3, v154
	v_or_b32_e32 v3, 19, v2
	s_nop 0
	v_cndmask_b32_e32 v78, v185, v78, vcc
	v_cmp_le_i32_e32 vcc, v84, v154
	v_or_b32_e32 v84, 51, v2
	s_nop 0
	v_cndmask_b32_e32 v62, v185, v62, vcc
	v_cmp_le_i32_e32 vcc, v3, v154
	v_or_b32_e32 v3, 24, v2
	s_nop 0
	v_cndmask_b32_e32 v79, v185, v79, vcc
	v_cmp_le_i32_e32 vcc, v84, v154
	v_or_b32_e32 v84, 56, v2
	s_nop 0
	v_cndmask_b32_e32 v63, v185, v63, vcc
	v_cmp_le_i32_e32 vcc, v3, v154
	v_or_b32_e32 v3, 25, v2
	s_nop 0
	v_cndmask_b32_e32 v80, v185, v80, vcc
	v_cmp_le_i32_e32 vcc, v84, v154
	v_or_b32_e32 v84, 57, v2
	s_nop 0
	v_cndmask_b32_e32 v64, v185, v64, vcc
	v_cmp_le_i32_e32 vcc, v3, v154
	v_or_b32_e32 v3, 26, v2
	s_nop 0
	v_cndmask_b32_e32 v81, v185, v81, vcc
	v_cmp_le_i32_e32 vcc, v84, v154
	v_or_b32_e32 v84, 58, v2
	s_nop 0
	v_cndmask_b32_e32 v65, v185, v65, vcc
	v_cmp_le_i32_e32 vcc, v3, v154
	v_or_b32_e32 v3, 27, v2
	v_or_b32_e32 v2, 59, v2
	v_cndmask_b32_e32 v82, v185, v82, vcc
	v_cmp_le_i32_e32 vcc, v84, v154
	s_nop 1
	v_cndmask_b32_e32 v66, v185, v66, vcc
	v_cmp_le_i32_e32 vcc, v3, v154
	s_nop 1
	v_cndmask_b32_e32 v83, v185, v83, vcc
	v_cmp_le_i32_e32 vcc, v2, v154
	s_nop 1
	v_cndmask_b32_e32 v67, v185, v67, vcc
.LBB0_796:
	s_nop 7
.LBB0_798:
	v_exp_f32_e32 v2, v68
	v_exp_f32_e32 v3, v69
	v_exp_f32_e32 v52, v52
	v_exp_f32_e32 v53, v53
	v_exp_f32_e32 v70, v70
	v_exp_f32_e32 v71, v71
	v_exp_f32_e32 v54, v54
	v_exp_f32_e32 v55, v55
	v_pk_add_f32 v[68:69], v[2:3], 0 op_sel_hi:[1,0]
	v_exp_f32_e32 v72, v72
	v_exp_f32_e32 v73, v73
	v_pk_add_f32 v[68:69], v[52:53], v[68:69]
	v_exp_f32_e32 v56, v56
	v_exp_f32_e32 v57, v57
	v_pk_add_f32 v[68:69], v[70:71], v[68:69]
	v_exp_f32_e32 v74, v74
	v_exp_f32_e32 v75, v75
	v_pk_add_f32 v[68:69], v[54:55], v[68:69]
	v_exp_f32_e32 v58, v58
	v_exp_f32_e32 v59, v59
	v_pk_add_f32 v[68:69], v[72:73], v[68:69]
	v_exp_f32_e32 v76, v76
	v_exp_f32_e32 v77, v77
	v_pk_add_f32 v[68:69], v[56:57], v[68:69]
	v_exp_f32_e32 v60, v60
	v_exp_f32_e32 v61, v61
	v_pk_add_f32 v[68:69], v[74:75], v[68:69]
	v_exp_f32_e32 v78, v78
	v_exp_f32_e32 v79, v79
	v_pk_add_f32 v[68:69], v[58:59], v[68:69]
	v_exp_f32_e32 v62, v62
	v_exp_f32_e32 v63, v63
	v_pk_add_f32 v[68:69], v[76:77], v[68:69]
	v_exp_f32_e32 v80, v80
	v_exp_f32_e32 v81, v81
	v_pk_add_f32 v[68:69], v[60:61], v[68:69]
	v_exp_f32_e32 v64, v64
	v_exp_f32_e32 v65, v65
	v_pk_add_f32 v[68:69], v[78:79], v[68:69]
	v_exp_f32_e32 v82, v82
	v_exp_f32_e32 v83, v83
	v_pk_add_f32 v[68:69], v[62:63], v[68:69]
	v_exp_f32_e32 v66, v66
	v_exp_f32_e32 v67, v67
	v_pk_add_f32 v[68:69], v[80:81], v[68:69]
	v_cvt_pk_bf16_f32 v88, v60, v61
	v_pk_add_f32 v[68:69], v[64:65], v[68:69]
	v_cvt_pk_bf16_f32 v89, v62, v63
	v_pk_add_f32 v[68:69], v[82:83], v[68:69]
	s_add_i32 s8, s17, 1
	v_pk_add_f32 v[68:69], v[66:67], v[68:69]
	s_cmp_lg_u32 s8, 3
	v_pk_add_f32 v[84:85], v[68:69], v[68:69] op_sel:[0,1] op_sel_hi:[1,0]
	v_cvt_pk_bf16_f32 v69, v70, v71
	v_cvt_pk_bf16_f32 v70, v72, v73
	v_cvt_pk_bf16_f32 v71, v74, v75
	v_cvt_pk_bf16_f32 v72, v76, v77
	v_cvt_pk_bf16_f32 v73, v78, v79
	v_cvt_pk_bf16_f32 v74, v80, v81
	v_cvt_pk_bf16_f32 v75, v82, v83
	v_cvt_pk_bf16_f32 v76, v52, v53
	v_cvt_pk_bf16_f32 v77, v54, v55
	v_cvt_pk_bf16_f32 v78, v56, v57
	v_cvt_pk_bf16_f32 v79, v58, v59
	ds_read_b128 v[52:55], v0 offset:9216
	ds_read_b128 v[56:59], v0 offset:9248
	ds_read_b128 v[60:63], v0 offset:9280
	ds_read_b128 v[80:83], v0 offset:9312
	s_cselect_b32 s22, s8, 0
	s_add_i32 s8, s22, 1
	s_cmp_lg_u32 s8, 3
	v_mov_b32_e32 v85, v84
	s_cselect_b32 s17, s8, 0
	s_nop 0
	v_permlane32_swap_b32_e32 v84, v85
	v_cvt_pk_bf16_f32 v68, v2, v3
	v_cvt_pk_bf16_f32 v90, v64, v65
	v_cvt_pk_bf16_f32 v91, v66, v67
	s_waitcnt lgkmcnt(3)
	v_mfma_f32_32x32x16_bf16 v[36:51], v[52:55], v[68:71], v[36:51]
	s_waitcnt lgkmcnt(2)
	v_mfma_f32_32x32x16_bf16 v[36:51], v[56:59], v[72:75], v[36:51]
	s_waitcnt lgkmcnt(1)
	v_mfma_f32_32x32x16_bf16 v[36:51], v[60:63], v[76:79], v[36:51]
	s_waitcnt lgkmcnt(0)
	v_mfma_f32_32x32x16_bf16 v[36:51], v[80:83], v[88:91], v[36:51]
	ds_read_b128 v[52:55], v0 offset:13824
	ds_read_b128 v[56:59], v0 offset:13856
	ds_read_b128 v[60:63], v0 offset:13888
	ds_read_b128 v[64:67], v0 offset:13920
	s_waitcnt lgkmcnt(3)
	v_mfma_f32_32x32x16_bf16 v[20:35], v[52:55], v[68:71], v[20:35]
	s_waitcnt lgkmcnt(2)
	v_mfma_f32_32x32x16_bf16 v[20:35], v[56:59], v[72:75], v[20:35]
	s_waitcnt lgkmcnt(1)
	v_mfma_f32_32x32x16_bf16 v[20:35], v[60:63], v[76:79], v[20:35]
	s_waitcnt lgkmcnt(0)
	v_mfma_f32_32x32x16_bf16 v[20:35], v[64:67], v[88:91], v[20:35]
	s_add_i32 s21, s13, -2
	s_cmp_ge_i32 s21, s12
	s_cbranch_scc1 .LBB0_802
	s_mul_i32 s8, s17, 0x4900
	s_add_i32 s10, s33, s8
	v_add3_u32 v0, s10, v171, v166
	s_waitcnt vmcnt(1)
	ds_write_b128 v0, v[132:135]
	s_waitcnt vmcnt(0)
	ds_write_b128 v0, v[136:139] offset:9216
	s_and_saveexec_b64 s[8:9], s[6:7]
	s_cbranch_execz .LBB0_801
	v_add_f32_e32 v170, v170, v223
	v_sub_f32_e32 v170, v155, v170
	v_cvt_pk_bf16_f32 v0, v170, 0
	v_and_b32_e32 v2, 0xffff, v0
	v_lshlrev_b32_e32 v0, 16, v0
	v_sub_f32_e32 v0, v170, v0
	v_cvt_pk_bf16_f32 v0, v0, 0
	v_lshl_or_b32 v0, v0, 16, v2
	v_mov_b32_e32 v2, v1
	v_mov_b32_e32 v3, v1
	v_add_u32_e32 v52, s10, v172
	ds_write_b128 v52, v[0:3] offset:128

.LBB0_802:
	s_waitcnt lgkmcnt(0)
	s_barrier
	v_add_f32_e32 v0, v84, v85
	s_add_i32 s10, s13, -3
	v_add_f32_e32 v175, v86, v0
	v_cmp_lt_f32_e32 vcc, 0x4b800000, v0
	s_cbranch_vccz .Lfox_noresc1
	s_nop 13
	v_log_f32_e32 v2, v0
	s_nop 0
	v_max_f32_e32 v2, 0, v2
	v_exp_f32_e64 v84, -v2
	v_sub_f32_e32 v4, v4, v2
	v_sub_f32_e32 v5, v5, v2
	v_sub_f32_e32 v6, v6, v2
	v_sub_f32_e32 v7, v7, v2
	v_sub_f32_e32 v8, v8, v2
	v_sub_f32_e32 v9, v9, v2
	v_sub_f32_e32 v10, v10, v2
	v_sub_f32_e32 v11, v11, v2
	v_sub_f32_e32 v12, v12, v2
	v_sub_f32_e32 v13, v13, v2
	v_sub_f32_e32 v14, v14, v2
	v_sub_f32_e32 v15, v15, v2
	v_sub_f32_e32 v16, v16, v2
	v_sub_f32_e32 v17, v17, v2
	v_sub_f32_e32 v18, v18, v2
	v_sub_f32_e32 v19, v19, v2
	v_mul_f32_e32 v175, v175, v84
	v_pk_mul_f32 v[20:21], v[20:21], v[84:85] op_sel_hi:[1,0]
	v_pk_mul_f32 v[22:23], v[22:23], v[84:85] op_sel_hi:[1,0]
	v_pk_mul_f32 v[24:25], v[24:25], v[84:85] op_sel_hi:[1,0]
	v_pk_mul_f32 v[26:27], v[26:27], v[84:85] op_sel_hi:[1,0]
	v_pk_mul_f32 v[28:29], v[28:29], v[84:85] op_sel_hi:[1,0]
	v_pk_mul_f32 v[30:31], v[30:31], v[84:85] op_sel_hi:[1,0]
	v_pk_mul_f32 v[32:33], v[32:33], v[84:85] op_sel_hi:[1,0]
	v_pk_mul_f32 v[34:35], v[34:35], v[84:85] op_sel_hi:[1,0]
	v_pk_mul_f32 v[36:37], v[36:37], v[84:85] op_sel_hi:[1,0]
	v_pk_mul_f32 v[38:39], v[38:39], v[84:85] op_sel_hi:[1,0]
	v_pk_mul_f32 v[40:41], v[40:41], v[84:85] op_sel_hi:[1,0]
	v_pk_mul_f32 v[42:43], v[42:43], v[84:85] op_sel_hi:[1,0]
	v_pk_mul_f32 v[44:45], v[44:45], v[84:85] op_sel_hi:[1,0]
	v_pk_mul_f32 v[46:47], v[46:47], v[84:85] op_sel_hi:[1,0]
	v_pk_mul_f32 v[48:49], v[48:49], v[84:85] op_sel_hi:[1,0]
	v_pk_mul_f32 v[50:51], v[50:51], v[84:85] op_sel_hi:[1,0]
	s_nop 1
.Lfox_noresc1:
	s_mov_b64 s[8:9], -1
	s_cmp_ge_i32 s10, s12
	s_mov_b64 s[10:11], -1
	s_cbranch_scc1 .LBB0_789
	s_cmp_ge_i32 s13, s12
	s_cbranch_scc1 .LBB0_807
	v_mov_b32_e32 v0, s19
	ds_read_b32 v0, v0 offset:16
	s_waitcnt lgkmcnt(0)
	v_lshlrev_b32_e32 v2, 6, v0
	v_add_u32_e32 v3, v2, v157
	v_mad_i64_i32 v[52:53], s[8:9], v3, s90, v[168:169]
	global_load_dwordx4 v[132:135], v[52:53], off offset:1024
	global_load_dwordx4 v[136:139], v[52:53], off offset:2048
	s_and_saveexec_b64 s[8:9], s[6:7]
	s_cbranch_execz .LBB0_806
	v_add_u32_e32 v2, v2, v159
	v_ashrrev_i32_e32 v3, 31, v2
	v_lshl_add_u64 v[2:3], v[2:3], 2, s[4:5]
	global_load_dword v170, v[2:3], off
	v_ashrrev_i32_e32 v0, 3, v0
	v_lshlrev_b32_e32 v0, 2, v0
	v_add_u32_e32 v0, s28, v0
	ds_read_b32 v223, v0

.LBB0_807:
	s_mulk_i32 s22, 0x4900
	v_add_u32_e32 v0, s22, v174
	ds_read_b128 v[52:55], v0
	ds_read_b128 v[56:59], v0 offset:32
	ds_read_b128 v[60:63], v0 offset:4608
	ds_read_b128 v[64:67], v0 offset:4640
	ds_read_b128 v[68:71], v0 offset:64
	ds_read_b128 v[72:75], v0 offset:96
	ds_read_b128 v[76:79], v0 offset:4672
	ds_read_b128 v[80:83], v0 offset:4704
	s_waitcnt lgkmcnt(7)
	v_mfma_f32_32x32x16_bf16 v[100:115], v[52:55], v[116:119], v[4:19]
	s_waitcnt lgkmcnt(5)
	v_mfma_f32_32x32x16_bf16 v[84:99], v[60:63], v[116:119], v[4:19]
	v_mfma_f32_32x32x16_bf16 v[100:115], v[56:59], v[120:123], v[100:115]
	ds_read_b128 v[52:55], v0 offset:128
	ds_read_b128 v[56:59], v0 offset:4736
	s_waitcnt lgkmcnt(6)
	v_mfma_f32_32x32x16_bf16 v[84:99], v[64:67], v[120:123], v[84:99]
	s_waitcnt lgkmcnt(5)
	v_mfma_f32_32x32x16_bf16 v[100:115], v[68:71], v[124:127], v[100:115]
	s_waitcnt lgkmcnt(3)
	v_mfma_f32_32x32x16_bf16 v[84:99], v[76:79], v[124:127], v[84:99]
	v_mfma_f32_32x32x16_bf16 v[100:115], v[72:75], v[128:131], v[100:115]
	s_waitcnt lgkmcnt(2)
	v_mfma_f32_32x32x16_bf16 v[84:99], v[80:83], v[128:131], v[84:99]
	s_waitcnt lgkmcnt(1)
	v_mfma_f32_32x32x16_bf16 v[100:115], v[52:55], v[148:151], v[100:115]
	s_waitcnt lgkmcnt(0)
	v_mfma_f32_32x32x16_bf16 v[84:99], v[56:59], v[148:151], v[84:99]
	v_mov_b32_e32 v2, s19
	ds_read_b32 v2, v2 offset:4
	s_waitcnt lgkmcnt(0)
	v_cmp_gt_i32_e32 vcc, s18, v2
	s_cbranch_vccnz .LBB0_809
	v_lshl_or_b32 v2, v2, 6, v158
	v_or_b32_e32 v3, 32, v2
	v_cmp_le_i32_e32 vcc, v2, v154
	v_or_b32_e32 v52, 34, v2
	s_nop 0
	v_cndmask_b32_e32 v100, v185, v100, vcc
	v_cmp_le_i32_e32 vcc, v3, v154
	v_or_b32_e32 v3, 33, v2
	s_nop 0
	v_cndmask_b32_e32 v84, v185, v84, vcc
	v_cmp_lt_i32_e32 vcc, v2, v154
	s_nop 1
	v_cndmask_b32_e32 v101, v185, v101, vcc
	v_cmp_le_i32_e32 vcc, v3, v154
	v_or_b32_e32 v3, 2, v2
	s_nop 0
	v_cndmask_b32_e32 v85, v185, v85, vcc
	v_cmp_le_i32_e32 vcc, v3, v154
	v_or_b32_e32 v3, 3, v2
	s_nop 0
	v_cndmask_b32_e32 v102, v185, v102, vcc
	v_cmp_le_i32_e32 vcc, v52, v154
	v_or_b32_e32 v52, 35, v2
	s_nop 0
	v_cndmask_b32_e32 v86, v185, v86, vcc
	v_cmp_le_i32_e32 vcc, v3, v154
	v_or_b32_e32 v3, 8, v2
	s_nop 0
	v_cndmask_b32_e32 v103, v185, v103, vcc
	v_cmp_le_i32_e32 vcc, v52, v154
	v_or_b32_e32 v52, 40, v2
	s_nop 0
	v_cndmask_b32_e32 v87, v185, v87, vcc
	v_cmp_le_i32_e32 vcc, v3, v154
	v_or_b32_e32 v3, 9, v2
	s_nop 0
	v_cndmask_b32_e32 v104, v185, v104, vcc
	v_cmp_le_i32_e32 vcc, v52, v154
	v_or_b32_e32 v52, 41, v2
	s_nop 0
	v_cndmask_b32_e32 v88, v185, v88, vcc
	v_cmp_le_i32_e32 vcc, v3, v154
	v_or_b32_e32 v3, 10, v2
	s_nop 0
	v_cndmask_b32_e32 v105, v185, v105, vcc
	v_cmp_le_i32_e32 vcc, v52, v154
	v_or_b32_e32 v52, 42, v2
	s_nop 0
	v_cndmask_b32_e32 v89, v185, v89, vcc
	v_cmp_le_i32_e32 vcc, v3, v154
	v_or_b32_e32 v3, 11, v2
	s_nop 0
	v_cndmask_b32_e32 v106, v185, v106, vcc
	v_cmp_le_i32_e32 vcc, v52, v154
	v_or_b32_e32 v52, 43, v2
	s_nop 0
	v_cndmask_b32_e32 v90, v185, v90, vcc
	v_cmp_le_i32_e32 vcc, v3, v154
	v_or_b32_e32 v3, 16, v2
	s_nop 0
	v_cndmask_b32_e32 v107, v185, v107, vcc
	v_cmp_le_i32_e32 vcc, v52, v154
	v_or_b32_e32 v52, 48, v2
	s_nop 0
	v_cndmask_b32_e32 v91, v185, v91, vcc
	v_cmp_le_i32_e32 vcc, v3, v154
	v_or_b32_e32 v3, 17, v2
	s_nop 0
	v_cndmask_b32_e32 v108, v185, v108, vcc
	v_cmp_le_i32_e32 vcc, v52, v154
	v_or_b32_e32 v52, 49, v2
	s_nop 0
	v_cndmask_b32_e32 v92, v185, v92, vcc
	v_cmp_le_i32_e32 vcc, v3, v154
	v_or_b32_e32 v3, 18, v2
	s_nop 0
	v_cndmask_b32_e32 v109, v185, v109, vcc
	v_cmp_le_i32_e32 vcc, v52, v154
	v_or_b32_e32 v52, 50, v2
	s_nop 0
	v_cndmask_b32_e32 v93, v185, v93, vcc
	v_cmp_le_i32_e32 vcc, v3, v154
	v_or_b32_e32 v3, 19, v2
	s_nop 0
	v_cndmask_b32_e32 v110, v185, v110, vcc
	v_cmp_le_i32_e32 vcc, v52, v154
	v_or_b32_e32 v52, 51, v2
	s_nop 0
	v_cndmask_b32_e32 v94, v185, v94, vcc
	v_cmp_le_i32_e32 vcc, v3, v154
	v_or_b32_e32 v3, 24, v2
	s_nop 0
	v_cndmask_b32_e32 v111, v185, v111, vcc
	v_cmp_le_i32_e32 vcc, v52, v154
	v_or_b32_e32 v52, 56, v2
	s_nop 0
	v_cndmask_b32_e32 v95, v185, v95, vcc
	v_cmp_le_i32_e32 vcc, v3, v154
	v_or_b32_e32 v3, 25, v2
	s_nop 0
	v_cndmask_b32_e32 v112, v185, v112, vcc
	v_cmp_le_i32_e32 vcc, v52, v154
	v_or_b32_e32 v52, 57, v2
	s_nop 0
	v_cndmask_b32_e32 v96, v185, v96, vcc
	v_cmp_le_i32_e32 vcc, v3, v154
	v_or_b32_e32 v3, 26, v2
	s_nop 0
	v_cndmask_b32_e32 v113, v185, v113, vcc
	v_cmp_le_i32_e32 vcc, v52, v154
	v_or_b32_e32 v52, 58, v2
	s_nop 0
	v_cndmask_b32_e32 v97, v185, v97, vcc
	v_cmp_le_i32_e32 vcc, v3, v154
	v_or_b32_e32 v3, 27, v2
	v_or_b32_e32 v2, 59, v2
	v_cndmask_b32_e32 v114, v185, v114, vcc
	v_cmp_le_i32_e32 vcc, v52, v154
	s_nop 1
	v_cndmask_b32_e32 v98, v185, v98, vcc
	v_cmp_le_i32_e32 vcc, v3, v154
	s_nop 1
	v_cndmask_b32_e32 v115, v185, v115, vcc
	v_cmp_le_i32_e32 vcc, v2, v154
	s_nop 1
	v_cndmask_b32_e32 v99, v185, v99, vcc
.LBB0_809:
	s_nop 7
.LBB0_811:
	v_mov_b32_e32 v176, v175

.Lsel_pre:
	s_mov_b32 s76, 0
	v_mad_i64_i32 v[30:31], vcc, v100, s90, v[30:31]
	v_mad_i64_i32 v[104:105], vcc, v100, s90, v[104:105]
	s_mov_b32 s81, 0
	s_movk_i32 s82, 0x4900
	s_mov_b32 s83, 0x9200
	v_mov_b32_e32 v0, s77
	ds_read_b32 v107, v0
	ds_read_b32 v160, v0 offset:4
	ds_read_b32 v184, v0 offset:8
	ds_read_b32 v182, v0 offset:12
	s_waitcnt lgkmcnt(0)
	v_readfirstlane_b32 s1, v107
	v_readfirstlane_b32 s0, v160
	v_readfirstlane_b32 s86, v184
	s_nop 1
	s_lshr_b32 s98, s1, 5
	s_and_b32 s98, s98, 3
	s_lshl_b32 s98, s98, 2
	v_add_u32_e32 v107, s98, v103
	ds_read_b32 v107, v107
	s_lshr_b32 s98, s0, 5
	s_and_b32 s98, s98, 3
	s_lshl_b32 s98, s98, 2
	v_add_u32_e32 v160, s98, v103
	ds_read_b32 v160, v160
	s_waitcnt lgkmcnt(0)
	s_and_b32 s98, s1, 31
	v_bfe_u32 v107, v107, s98, 1
	v_cmp_eq_u32_e64 s[72:73], 0, v107
	s_and_b32 s98, s0, 31
	v_bfe_u32 v160, v160, s98, 1
	v_cmp_eq_u32_e64 s[100:101], 0, v160
	s_cmp_ge_u32 s79, 2
	s_cbranch_scc1 .Lsel_pre_n1
	s_mov_b64 s[100:101], -1

.Lsel_step_0:
	v_readfirstlane_b32 s0, v182
	s_add_u32 s1, s76, 3
	s_cmp_lt_u32 s1, s79
	s_cbranch_scc0 .Lsel_nogl_0
	s_mul_i32 s98, s0, 0x99000
	s_mov_b32 s99, 0
	v_lshl_add_u64 v[18:19], v[30:31], 0, s[98:99]
	v_lshl_add_u64 v[22:23], v[104:105], 0, s[98:99]
	global_load_dwordx4 v[18:21], v[18:19], off
	s_nop 0
	global_load_dwordx4 v[22:25], v[22:23], off
.Lsel_nogl_0:
	s_lshr_b32 s98, s86, 5
	s_and_b32 s98, s98, 3
	s_lshl_b32 s98, s98, 2
	v_add_u32_e32 v184, s98, v103
	ds_read_b32 v184, v184
	s_cmp_lg_u64 s[100:101], -1
	s_cbranch_scc0 .Lsel_noN_0
	s_cmp_lg_u64 s[72:73], -1
	s_cbranch_scc0 .Lsel_Nonly_0
	v_add_u32_e32 v0, s82, v208
	ds_read_b128 v[108:111], v0
	ds_read_b128 v[112:115], v0 offset:4608
	ds_read_b128 v[116:119], v0 offset:32
	ds_read_b128 v[120:123], v0 offset:4640
	s_add_u32 s1, s76, 1
	s_cmp_lg_u32 s1, s79
	s_cbranch_scc1 .Lsel_nodiag_0b
	v_cndmask_b32_e64 v80, v80, v185, s[6:7]
	v_cndmask_b32_e64 v64, v64, v185, s[8:9]
	v_cndmask_b32_e64 v81, v185, v81, s[10:11]
	v_cndmask_b32_e64 v65, v65, v185, s[12:13]
	v_cndmask_b32_e64 v82, v82, v185, s[14:15]
	v_cndmask_b32_e64 v66, v66, v185, s[16:17]
	v_cndmask_b32_e64 v83, v83, v185, s[18:19]
	v_cndmask_b32_e64 v67, v67, v185, s[20:21]
	v_cndmask_b32_e64 v84, v84, v185, s[22:23]
	v_cndmask_b32_e64 v68, v68, v185, s[24:25]
	v_cndmask_b32_e64 v85, v85, v185, s[26:27]
	v_cndmask_b32_e64 v69, v69, v185, s[28:29]
	v_cndmask_b32_e64 v86, v86, v185, s[30:31]
	v_cndmask_b32_e64 v70, v70, v185, s[34:35]
	v_cndmask_b32_e64 v87, v87, v185, s[36:37]
	v_cndmask_b32_e64 v71, v71, v185, s[38:39]
	v_cndmask_b32_e64 v88, v88, v185, s[40:41]
	v_cndmask_b32_e64 v72, v72, v185, s[42:43]
	v_cndmask_b32_e64 v89, v89, v185, s[44:45]
	v_cndmask_b32_e64 v73, v73, v185, s[46:47]
	v_cndmask_b32_e64 v90, v90, v185, s[48:49]
	v_cndmask_b32_e64 v74, v74, v185, s[50:51]
	v_cndmask_b32_e64 v91, v91, v185, s[52:53]
	v_cndmask_b32_e64 v75, v75, v185, s[54:55]
	v_cndmask_b32_e64 v92, v92, v185, s[56:57]
	v_cndmask_b32_e64 v76, v76, v185, s[58:59]
	v_cndmask_b32_e64 v93, v93, v185, s[60:61]
	v_cndmask_b32_e64 v77, v77, v185, s[62:63]
	v_cndmask_b32_e64 v94, v94, v185, s[64:65]
	v_cndmask_b32_e64 v78, v78, v185, s[66:67]
	v_cndmask_b32_e64 v95, v95, v185, s[68:69]
	v_cndmask_b32_e64 v79, v79, v185, s[70:71]

.Lsel_step_1:
	v_readfirstlane_b32 s0, v182
	s_add_u32 s1, s76, 3
	s_cmp_lt_u32 s1, s79
	s_cbranch_scc0 .Lsel_nogl_1
	s_mul_i32 s98, s0, 0x99000
	s_mov_b32 s99, 0
	v_lshl_add_u64 v[26:27], v[30:31], 0, s[98:99]
	v_lshl_add_u64 v[96:97], v[104:105], 0, s[98:99]
	global_load_dwordx4 v[26:29], v[26:27], off
	s_nop 0
	global_load_dwordx4 v[96:99], v[96:97], off
.Lsel_nogl_1:
	s_lshr_b32 s98, s86, 5
	s_and_b32 s98, s98, 3
	s_lshl_b32 s98, s98, 2
	v_add_u32_e32 v184, s98, v103
	ds_read_b32 v184, v184
	s_cmp_lg_u64 s[100:101], -1
	s_cbranch_scc0 .Lsel_noN_1
	s_cmp_lg_u64 s[72:73], -1
	s_cbranch_scc0 .Lsel_Nonly_1
	v_add_u32_e32 v0, s82, v208
	ds_read_b128 v[108:111], v0
	ds_read_b128 v[112:115], v0 offset:4608
	ds_read_b128 v[116:119], v0 offset:32
	ds_read_b128 v[120:123], v0 offset:4640
	s_add_u32 s1, s76, 1
	s_cmp_lg_u32 s1, s79
	s_cbranch_scc1 .Lsel_nodiag_1b
	v_cndmask_b32_e64 v238, v238, v185, s[6:7]
	v_cndmask_b32_e64 v222, v222, v185, s[8:9]
	v_cndmask_b32_e64 v239, v185, v239, s[10:11]
	v_cndmask_b32_e64 v223, v223, v185, s[12:13]
	v_cndmask_b32_e64 v240, v240, v185, s[14:15]
	v_cndmask_b32_e64 v224, v224, v185, s[16:17]
	v_cndmask_b32_e64 v241, v241, v185, s[18:19]
	v_cndmask_b32_e64 v225, v225, v185, s[20:21]
	v_cndmask_b32_e64 v242, v242, v185, s[22:23]
	v_cndmask_b32_e64 v226, v226, v185, s[24:25]
	v_cndmask_b32_e64 v243, v243, v185, s[26:27]
	v_cndmask_b32_e64 v227, v227, v185, s[28:29]
	v_cndmask_b32_e64 v244, v244, v185, s[30:31]
	v_cndmask_b32_e64 v228, v228, v185, s[34:35]
	v_cndmask_b32_e64 v245, v245, v185, s[36:37]
	v_cndmask_b32_e64 v229, v229, v185, s[38:39]
	v_cndmask_b32_e64 v246, v246, v185, s[40:41]
	v_cndmask_b32_e64 v230, v230, v185, s[42:43]
	v_cndmask_b32_e64 v247, v247, v185, s[44:45]
	v_cndmask_b32_e64 v231, v231, v185, s[46:47]
	v_cndmask_b32_e64 v248, v248, v185, s[48:49]
	v_cndmask_b32_e64 v232, v232, v185, s[50:51]
	v_cndmask_b32_e64 v249, v249, v185, s[52:53]
	v_cndmask_b32_e64 v233, v233, v185, s[54:55]
	v_cndmask_b32_e64 v250, v250, v185, s[56:57]
	v_cndmask_b32_e64 v234, v234, v185, s[58:59]
	v_cndmask_b32_e64 v251, v251, v185, s[60:61]
	v_cndmask_b32_e64 v235, v235, v185, s[62:63]
	v_cndmask_b32_e64 v252, v252, v185, s[64:65]
	v_cndmask_b32_e64 v236, v236, v185, s[66:67]
	v_cndmask_b32_e64 v253, v253, v185, s[68:69]
	v_cndmask_b32_e64 v237, v237, v185, s[70:71]
